# ssd_passC second pass (per-token rstd rescale) rewritten: all 64 bf16 loads in flight, counted vmcnt, instead of 32 serialized load-wait-store round trips
# baseline (speedup 1.0000x reference)
.LBB0_1056:
	v_mov_b32_dpp v0, v32 row_ror:8 row_mask:0xf bank_mask:0xf bound_ctrl:1
	v_mov_b32_dpp v1, v33 row_ror:8 row_mask:0xf bank_mask:0xf bound_ctrl:1
	v_mov_b32_dpp v2, v16 row_ror:8 row_mask:0xf bank_mask:0xf bound_ctrl:1
	v_mov_b32_dpp v3, v17 row_ror:8 row_mask:0xf bank_mask:0xf bound_ctrl:1
	s_movk_i32 s0, 0xffc0
	v_and_or_b32 v6, v20, s0, v22
	ds_read_b128 v[10:13], v6 offset:46592
	v_pk_add_f32 v[0:1], v[32:33], v[0:1]
	v_pk_add_f32 v[2:3], v[16:17], v[2:3]
	v_lshlrev_b32_e32 v148, 1, v18
	v_readlane_b32 s2, v247, 30
	v_readlane_b32 s3, v247, 31
	v_mov_b32_dpp v6, v0 row_ror:4 row_mask:0xf bank_mask:0xf bound_ctrl:1
	v_mov_b32_dpp v7, v1 row_ror:4 row_mask:0xf bank_mask:0xf bound_ctrl:1
	v_mov_b32_dpp v8, v2 row_ror:4 row_mask:0xf bank_mask:0xf bound_ctrl:1
	v_mov_b32_dpp v9, v3 row_ror:4 row_mask:0xf bank_mask:0xf bound_ctrl:1
	v_pk_add_f32 v[0:1], v[0:1], v[6:7]
	v_pk_add_f32 v[2:3], v[2:3], v[8:9]
	s_mov_b32 s6, 0x3b800000
	s_mov_b32 s4, 0x800000
	v_mov_b32_dpp v6, v0 row_ror:2 row_mask:0xf bank_mask:0xf bound_ctrl:1
	v_mov_b32_dpp v7, v1 row_ror:2 row_mask:0xf bank_mask:0xf bound_ctrl:1
	v_mov_b32_dpp v8, v2 row_ror:2 row_mask:0xf bank_mask:0xf bound_ctrl:1
	v_mov_b32_dpp v9, v3 row_ror:2 row_mask:0xf bank_mask:0xf bound_ctrl:1
	v_pk_add_f32 v[0:1], v[0:1], v[6:7]
	v_pk_add_f32 v[2:3], v[2:3], v[8:9]
	s_mov_b32 s0, 0x358637bd
	v_mov_b32_e32 v4, s0
	v_mov_b32_dpp v6, v0 row_ror:1 row_mask:0xf bank_mask:0xf bound_ctrl:1
	v_mov_b32_dpp v7, v1 row_ror:1 row_mask:0xf bank_mask:0xf bound_ctrl:1
	v_mov_b32_dpp v8, v2 row_ror:1 row_mask:0xf bank_mask:0xf bound_ctrl:1
	v_mov_b32_dpp v9, v3 row_ror:1 row_mask:0xf bank_mask:0xf bound_ctrl:1
	v_pk_add_f32 v[0:1], v[0:1], v[6:7]
	v_pk_add_f32 v[2:3], v[2:3], v[8:9]
	s_nop 0
	v_fma_f32 v0, v0, s6, v4
	v_fma_f32 v1, v1, s6, v4
	v_fma_f32 v2, v2, s6, v4
	v_fma_f32 v3, v3, s6, v4
	v_cmp_gt_f32_e32 vcc, s4, v0
	v_mul_f32_e32 v6, 0x4b800000, v0
	s_nop 1
	v_cndmask_b32_e32 v0, v0, v6, vcc
	v_rsq_f32_e32 v0, v0
	s_nop 0
	v_mul_f32_e32 v6, 0x45800000, v0
	v_cndmask_b32_e32 v24, v0, v6, vcc
	v_cmp_gt_f32_e32 vcc, s4, v1
	v_mul_f32_e32 v6, 0x4b800000, v1
	s_nop 1
	v_cndmask_b32_e32 v1, v1, v6, vcc
	v_rsq_f32_e32 v1, v1
	s_nop 0
	v_mul_f32_e32 v6, 0x45800000, v1
	v_cndmask_b32_e32 v25, v1, v6, vcc
	v_cmp_gt_f32_e32 vcc, s4, v2
	v_mul_f32_e32 v6, 0x4b800000, v2
	s_nop 1
	v_cndmask_b32_e32 v2, v2, v6, vcc
	v_rsq_f32_e32 v2, v2
	s_nop 0
	v_mul_f32_e32 v6, 0x45800000, v2
	v_cndmask_b32_e32 v26, v2, v6, vcc
	v_cmp_gt_f32_e32 vcc, s4, v3
	v_mul_f32_e32 v6, 0x4b800000, v3
	s_nop 1
	v_cndmask_b32_e32 v3, v3, v6, vcc
	v_rsq_f32_e32 v3, v3
	s_nop 0
	v_mul_f32_e32 v6, 0x45800000, v3
	v_cndmask_b32_e32 v27, v3, v6, vcc
	s_waitcnt lgkmcnt(0)
	v_ashrrev_i32_e32 v15, 31, v10
	v_mov_b32_e32 v14, v10
	v_ashrrev_i32_e32 v19, 31, v11
	v_mov_b32_e32 v18, v11
	v_ashrrev_i32_e32 v21, 31, v12
	v_mov_b32_e32 v20, v12
	v_ashrrev_i32_e32 v23, 31, v13
	v_mov_b32_e32 v22, v13
	v_lshlrev_b64 v[14:15], 11, v[14:15]
	v_lshlrev_b64 v[18:19], 11, v[18:19]
	v_lshlrev_b64 v[20:21], 11, v[20:21]
	v_lshlrev_b64 v[22:23], 11, v[22:23]
	v_lshl_add_u64 v[14:15], s[2:3], 0, v[14:15]
	v_lshl_add_u64 v[18:19], s[2:3], 0, v[18:19]
	v_lshl_add_u64 v[20:21], s[2:3], 0, v[20:21]
	v_lshl_add_u64 v[22:23], s[2:3], 0, v[22:23]
	v_lshl_add_u64 v[14:15], v[14:15], 0, v[148:149]
	v_lshl_add_u64 v[18:19], v[18:19], 0, v[148:149]
	v_lshl_add_u64 v[20:21], v[20:21], 0, v[148:149]
	v_lshl_add_u64 v[22:23], v[22:23], 0, v[148:149]
	global_load_ushort v114, v[14:15], off offset:512
	global_load_ushort v115, v[14:15], off offset:544
	global_load_ushort v116, v[14:15], off offset:576
	global_load_ushort v117, v[14:15], off offset:608
	global_load_ushort v118, v[14:15], off offset:640
	global_load_ushort v119, v[14:15], off offset:672
	global_load_ushort v120, v[14:15], off offset:704
	global_load_ushort v121, v[14:15], off offset:736
	global_load_ushort v122, v[14:15], off offset:768
	global_load_ushort v123, v[14:15], off offset:800
	global_load_ushort v124, v[14:15], off offset:832
	global_load_ushort v125, v[14:15], off offset:864
	global_load_ushort v126, v[14:15], off offset:896
	global_load_ushort v127, v[14:15], off offset:928
	global_load_ushort v128, v[14:15], off offset:960
	global_load_ushort v129, v[14:15], off offset:992
	global_load_ushort v130, v[18:19], off offset:512
	global_load_ushort v131, v[18:19], off offset:544
	global_load_ushort v132, v[18:19], off offset:576
	global_load_ushort v133, v[18:19], off offset:608
	global_load_ushort v134, v[18:19], off offset:640
	global_load_ushort v135, v[18:19], off offset:672
	global_load_ushort v136, v[18:19], off offset:704
	global_load_ushort v137, v[18:19], off offset:736
	global_load_ushort v138, v[18:19], off offset:768
	global_load_ushort v139, v[18:19], off offset:800
	global_load_ushort v140, v[18:19], off offset:832
	global_load_ushort v141, v[18:19], off offset:864
	global_load_ushort v142, v[18:19], off offset:896
	global_load_ushort v143, v[18:19], off offset:928
	global_load_ushort v152, v[18:19], off offset:960
	global_load_ushort v153, v[18:19], off offset:992
	global_load_ushort v154, v[20:21], off offset:512
	global_load_ushort v155, v[20:21], off offset:544
	global_load_ushort v156, v[20:21], off offset:576
	global_load_ushort v157, v[20:21], off offset:608
	global_load_ushort v158, v[20:21], off offset:640
	global_load_ushort v159, v[20:21], off offset:672
	global_load_ushort v160, v[20:21], off offset:704
	global_load_ushort v161, v[20:21], off offset:736
	global_load_ushort v162, v[20:21], off offset:768
	global_load_ushort v163, v[20:21], off offset:800
	global_load_ushort v164, v[20:21], off offset:832
	global_load_ushort v165, v[20:21], off offset:864
	global_load_ushort v166, v[20:21], off offset:896
	global_load_ushort v167, v[20:21], off offset:928
	global_load_ushort v168, v[20:21], off offset:960
	global_load_ushort v169, v[20:21], off offset:992
	global_load_ushort v170, v[22:23], off offset:512
	global_load_ushort v171, v[22:23], off offset:544
	global_load_ushort v204, v[22:23], off offset:576
	global_load_ushort v205, v[22:23], off offset:608
	global_load_ushort v206, v[22:23], off offset:640
	global_load_ushort v207, v[22:23], off offset:672
	global_load_ushort v208, v[22:23], off offset:704
	global_load_ushort v209, v[22:23], off offset:736
	global_load_ushort v210, v[22:23], off offset:768
	global_load_ushort v211, v[22:23], off offset:800
	global_load_ushort v212, v[22:23], off offset:832
	global_load_ushort v213, v[22:23], off offset:864
	global_load_ushort v214, v[22:23], off offset:896
	global_load_ushort v215, v[22:23], off offset:928
	global_load_ushort v216, v[22:23], off offset:960
	global_load_ushort v217, v[22:23], off offset:992
	v_readlane_b32 s80, v247, 59
	v_readlane_b32 s84, v250, 41
	v_readlane_b32 s88, v249, 13
	v_readlane_b32 s90, v247, 63
	v_readlane_b32 s94, v251, 6
	v_readlane_b32 s78, v247, 55
	v_readlane_b32 s26, v249, 25
	v_readlane_b32 s81, v247, 60
	v_readlane_b32 s82, v247, 61
	v_readlane_b32 s83, v247, 62
	v_readlane_b32 s85, v250, 42
	v_readlane_b32 s89, v249, 14
	v_readlane_b32 s91, v251, 0
	v_readlane_b32 s92, v251, 1
	v_readlane_b32 s93, v251, 2
	v_readlane_b32 s95, v251, 7
	v_readlane_b32 s96, v251, 8
	v_readlane_b32 s79, v247, 56
	v_readlane_b32 s97, v251, 9
	s_movk_i32 s87, 0x48
	s_movk_i32 s86, 0xeff
	v_readlane_b32 s27, v249, 26
	v_readlane_b32 s28, v249, 30
	s_waitcnt vmcnt(63)
	v_lshlrev_b32_e32 v114, 16, v114
	v_mul_f32_e32 v114, v24, v114
	v_bfe_u32 v218, v114, 16, 1
	v_add3_u32 v114, v114, v218, s52
	global_store_short_d16_hi v[14:15], v114, off offset:512
	s_waitcnt vmcnt(63)
	v_lshlrev_b32_e32 v115, 16, v115
	v_mul_f32_e32 v115, v24, v115
	v_bfe_u32 v219, v115, 16, 1
	v_add3_u32 v115, v115, v219, s52
	global_store_short_d16_hi v[14:15], v115, off offset:544
	s_waitcnt vmcnt(63)
	v_lshlrev_b32_e32 v116, 16, v116
	v_mul_f32_e32 v116, v24, v116
	v_bfe_u32 v220, v116, 16, 1
	v_add3_u32 v116, v116, v220, s52
	global_store_short_d16_hi v[14:15], v116, off offset:576
	s_waitcnt vmcnt(63)
	v_lshlrev_b32_e32 v117, 16, v117
	v_mul_f32_e32 v117, v24, v117
	v_bfe_u32 v221, v117, 16, 1
	v_add3_u32 v117, v117, v221, s52
	global_store_short_d16_hi v[14:15], v117, off offset:608
	s_waitcnt vmcnt(63)
	v_lshlrev_b32_e32 v118, 16, v118
	v_mul_f32_e32 v118, v24, v118
	v_bfe_u32 v218, v118, 16, 1
	v_add3_u32 v118, v118, v218, s52
	global_store_short_d16_hi v[14:15], v118, off offset:640
	s_waitcnt vmcnt(63)
	v_lshlrev_b32_e32 v119, 16, v119
	v_mul_f32_e32 v119, v24, v119
	v_bfe_u32 v219, v119, 16, 1
	v_add3_u32 v119, v119, v219, s52
	global_store_short_d16_hi v[14:15], v119, off offset:672
	s_waitcnt vmcnt(63)
	v_lshlrev_b32_e32 v120, 16, v120
	v_mul_f32_e32 v120, v24, v120
	v_bfe_u32 v220, v120, 16, 1
	v_add3_u32 v120, v120, v220, s52
	global_store_short_d16_hi v[14:15], v120, off offset:704
	s_waitcnt vmcnt(63)
	v_lshlrev_b32_e32 v121, 16, v121
	v_mul_f32_e32 v121, v24, v121
	v_bfe_u32 v221, v121, 16, 1
	v_add3_u32 v121, v121, v221, s52
	global_store_short_d16_hi v[14:15], v121, off offset:736
	s_waitcnt vmcnt(63)
	v_lshlrev_b32_e32 v122, 16, v122
	v_mul_f32_e32 v122, v24, v122
	v_bfe_u32 v218, v122, 16, 1
	v_add3_u32 v122, v122, v218, s52
	global_store_short_d16_hi v[14:15], v122, off offset:768
	s_waitcnt vmcnt(63)
	v_lshlrev_b32_e32 v123, 16, v123
	v_mul_f32_e32 v123, v24, v123
	v_bfe_u32 v219, v123, 16, 1
	v_add3_u32 v123, v123, v219, s52
	global_store_short_d16_hi v[14:15], v123, off offset:800
	s_waitcnt vmcnt(63)
	v_lshlrev_b32_e32 v124, 16, v124
	v_mul_f32_e32 v124, v24, v124
	v_bfe_u32 v220, v124, 16, 1
	v_add3_u32 v124, v124, v220, s52
	global_store_short_d16_hi v[14:15], v124, off offset:832
	s_waitcnt vmcnt(63)
	v_lshlrev_b32_e32 v125, 16, v125
	v_mul_f32_e32 v125, v24, v125
	v_bfe_u32 v221, v125, 16, 1
	v_add3_u32 v125, v125, v221, s52
	global_store_short_d16_hi v[14:15], v125, off offset:864
	s_waitcnt vmcnt(63)
	v_lshlrev_b32_e32 v126, 16, v126
	v_mul_f32_e32 v126, v24, v126
	v_bfe_u32 v218, v126, 16, 1
	v_add3_u32 v126, v126, v218, s52
	global_store_short_d16_hi v[14:15], v126, off offset:896
	s_waitcnt vmcnt(63)
	v_lshlrev_b32_e32 v127, 16, v127
	v_mul_f32_e32 v127, v24, v127
	v_bfe_u32 v219, v127, 16, 1
	v_add3_u32 v127, v127, v219, s52
	global_store_short_d16_hi v[14:15], v127, off offset:928
	s_waitcnt vmcnt(63)
	v_lshlrev_b32_e32 v128, 16, v128
	v_mul_f32_e32 v128, v24, v128
	v_bfe_u32 v220, v128, 16, 1
	v_add3_u32 v128, v128, v220, s52
	global_store_short_d16_hi v[14:15], v128, off offset:960
	s_waitcnt vmcnt(63)
	v_lshlrev_b32_e32 v129, 16, v129
	v_mul_f32_e32 v129, v24, v129
	v_bfe_u32 v221, v129, 16, 1
	v_add3_u32 v129, v129, v221, s52
	global_store_short_d16_hi v[14:15], v129, off offset:992
	s_waitcnt vmcnt(63)
	v_lshlrev_b32_e32 v130, 16, v130
	v_mul_f32_e32 v130, v25, v130
	v_bfe_u32 v218, v130, 16, 1
	v_add3_u32 v130, v130, v218, s52
	global_store_short_d16_hi v[18:19], v130, off offset:512
	s_waitcnt vmcnt(63)
	v_lshlrev_b32_e32 v131, 16, v131
	v_mul_f32_e32 v131, v25, v131
	v_bfe_u32 v219, v131, 16, 1
	v_add3_u32 v131, v131, v219, s52
	global_store_short_d16_hi v[18:19], v131, off offset:544
	s_waitcnt vmcnt(63)
	v_lshlrev_b32_e32 v132, 16, v132
	v_mul_f32_e32 v132, v25, v132
	v_bfe_u32 v220, v132, 16, 1
	v_add3_u32 v132, v132, v220, s52
	global_store_short_d16_hi v[18:19], v132, off offset:576
	s_waitcnt vmcnt(63)
	v_lshlrev_b32_e32 v133, 16, v133
	v_mul_f32_e32 v133, v25, v133
	v_bfe_u32 v221, v133, 16, 1
	v_add3_u32 v133, v133, v221, s52
	global_store_short_d16_hi v[18:19], v133, off offset:608
	s_waitcnt vmcnt(63)
	v_lshlrev_b32_e32 v134, 16, v134
	v_mul_f32_e32 v134, v25, v134
	v_bfe_u32 v218, v134, 16, 1
	v_add3_u32 v134, v134, v218, s52
	global_store_short_d16_hi v[18:19], v134, off offset:640
	s_waitcnt vmcnt(63)
	v_lshlrev_b32_e32 v135, 16, v135
	v_mul_f32_e32 v135, v25, v135
	v_bfe_u32 v219, v135, 16, 1
	v_add3_u32 v135, v135, v219, s52
	global_store_short_d16_hi v[18:19], v135, off offset:672
	s_waitcnt vmcnt(63)
	v_lshlrev_b32_e32 v136, 16, v136
	v_mul_f32_e32 v136, v25, v136
	v_bfe_u32 v220, v136, 16, 1
	v_add3_u32 v136, v136, v220, s52
	global_store_short_d16_hi v[18:19], v136, off offset:704
	s_waitcnt vmcnt(63)
	v_lshlrev_b32_e32 v137, 16, v137
	v_mul_f32_e32 v137, v25, v137
	v_bfe_u32 v221, v137, 16, 1
	v_add3_u32 v137, v137, v221, s52
	global_store_short_d16_hi v[18:19], v137, off offset:736
	s_waitcnt vmcnt(63)
	v_lshlrev_b32_e32 v138, 16, v138
	v_mul_f32_e32 v138, v25, v138
	v_bfe_u32 v218, v138, 16, 1
	v_add3_u32 v138, v138, v218, s52
	global_store_short_d16_hi v[18:19], v138, off offset:768
	s_waitcnt vmcnt(63)
	v_lshlrev_b32_e32 v139, 16, v139
	v_mul_f32_e32 v139, v25, v139
	v_bfe_u32 v219, v139, 16, 1
	v_add3_u32 v139, v139, v219, s52
	global_store_short_d16_hi v[18:19], v139, off offset:800
	s_waitcnt vmcnt(63)
	v_lshlrev_b32_e32 v140, 16, v140
	v_mul_f32_e32 v140, v25, v140
	v_bfe_u32 v220, v140, 16, 1
	v_add3_u32 v140, v140, v220, s52
	global_store_short_d16_hi v[18:19], v140, off offset:832
	s_waitcnt vmcnt(63)
	v_lshlrev_b32_e32 v141, 16, v141
	v_mul_f32_e32 v141, v25, v141
	v_bfe_u32 v221, v141, 16, 1
	v_add3_u32 v141, v141, v221, s52
	global_store_short_d16_hi v[18:19], v141, off offset:864
	s_waitcnt vmcnt(63)
	v_lshlrev_b32_e32 v142, 16, v142
	v_mul_f32_e32 v142, v25, v142
	v_bfe_u32 v218, v142, 16, 1
	v_add3_u32 v142, v142, v218, s52
	global_store_short_d16_hi v[18:19], v142, off offset:896
	s_waitcnt vmcnt(63)
	v_lshlrev_b32_e32 v143, 16, v143
	v_mul_f32_e32 v143, v25, v143
	v_bfe_u32 v219, v143, 16, 1
	v_add3_u32 v143, v143, v219, s52
	global_store_short_d16_hi v[18:19], v143, off offset:928
	s_waitcnt vmcnt(63)
	v_lshlrev_b32_e32 v152, 16, v152
	v_mul_f32_e32 v152, v25, v152
	v_bfe_u32 v220, v152, 16, 1
	v_add3_u32 v152, v152, v220, s52
	global_store_short_d16_hi v[18:19], v152, off offset:960
	s_waitcnt vmcnt(63)
	v_lshlrev_b32_e32 v153, 16, v153
	v_mul_f32_e32 v153, v25, v153
	v_bfe_u32 v221, v153, 16, 1
	v_add3_u32 v153, v153, v221, s52
	global_store_short_d16_hi v[18:19], v153, off offset:992
	s_waitcnt vmcnt(63)
	v_lshlrev_b32_e32 v154, 16, v154
	v_mul_f32_e32 v154, v26, v154
	v_bfe_u32 v218, v154, 16, 1
	v_add3_u32 v154, v154, v218, s52
	global_store_short_d16_hi v[20:21], v154, off offset:512
	s_waitcnt vmcnt(63)
	v_lshlrev_b32_e32 v155, 16, v155
	v_mul_f32_e32 v155, v26, v155
	v_bfe_u32 v219, v155, 16, 1
	v_add3_u32 v155, v155, v219, s52
	global_store_short_d16_hi v[20:21], v155, off offset:544
	s_waitcnt vmcnt(63)
	v_lshlrev_b32_e32 v156, 16, v156
	v_mul_f32_e32 v156, v26, v156
	v_bfe_u32 v220, v156, 16, 1
	v_add3_u32 v156, v156, v220, s52
	global_store_short_d16_hi v[20:21], v156, off offset:576
	s_waitcnt vmcnt(63)
	v_lshlrev_b32_e32 v157, 16, v157
	v_mul_f32_e32 v157, v26, v157
	v_bfe_u32 v221, v157, 16, 1
	v_add3_u32 v157, v157, v221, s52
	global_store_short_d16_hi v[20:21], v157, off offset:608
	s_waitcnt vmcnt(63)
	v_lshlrev_b32_e32 v158, 16, v158
	v_mul_f32_e32 v158, v26, v158
	v_bfe_u32 v218, v158, 16, 1
	v_add3_u32 v158, v158, v218, s52
	global_store_short_d16_hi v[20:21], v158, off offset:640
	s_waitcnt vmcnt(63)
	v_lshlrev_b32_e32 v159, 16, v159
	v_mul_f32_e32 v159, v26, v159
	v_bfe_u32 v219, v159, 16, 1
	v_add3_u32 v159, v159, v219, s52
	global_store_short_d16_hi v[20:21], v159, off offset:672
	s_waitcnt vmcnt(63)
	v_lshlrev_b32_e32 v160, 16, v160
	v_mul_f32_e32 v160, v26, v160
	v_bfe_u32 v220, v160, 16, 1
	v_add3_u32 v160, v160, v220, s52
	global_store_short_d16_hi v[20:21], v160, off offset:704
	s_waitcnt vmcnt(63)
	v_lshlrev_b32_e32 v161, 16, v161
	v_mul_f32_e32 v161, v26, v161
	v_bfe_u32 v221, v161, 16, 1
	v_add3_u32 v161, v161, v221, s52
	global_store_short_d16_hi v[20:21], v161, off offset:736
	s_waitcnt vmcnt(63)
	v_lshlrev_b32_e32 v162, 16, v162
	v_mul_f32_e32 v162, v26, v162
	v_bfe_u32 v218, v162, 16, 1
	v_add3_u32 v162, v162, v218, s52
	global_store_short_d16_hi v[20:21], v162, off offset:768
	s_waitcnt vmcnt(63)
	v_lshlrev_b32_e32 v163, 16, v163
	v_mul_f32_e32 v163, v26, v163
	v_bfe_u32 v219, v163, 16, 1
	v_add3_u32 v163, v163, v219, s52
	global_store_short_d16_hi v[20:21], v163, off offset:800
	s_waitcnt vmcnt(63)
	v_lshlrev_b32_e32 v164, 16, v164
	v_mul_f32_e32 v164, v26, v164
	v_bfe_u32 v220, v164, 16, 1
	v_add3_u32 v164, v164, v220, s52
	global_store_short_d16_hi v[20:21], v164, off offset:832
	s_waitcnt vmcnt(63)
	v_lshlrev_b32_e32 v165, 16, v165
	v_mul_f32_e32 v165, v26, v165
	v_bfe_u32 v221, v165, 16, 1
	v_add3_u32 v165, v165, v221, s52
	global_store_short_d16_hi v[20:21], v165, off offset:864
	s_waitcnt vmcnt(63)
	v_lshlrev_b32_e32 v166, 16, v166
	v_mul_f32_e32 v166, v26, v166
	v_bfe_u32 v218, v166, 16, 1
	v_add3_u32 v166, v166, v218, s52
	global_store_short_d16_hi v[20:21], v166, off offset:896
	s_waitcnt vmcnt(63)
	v_lshlrev_b32_e32 v167, 16, v167
	v_mul_f32_e32 v167, v26, v167
	v_bfe_u32 v219, v167, 16, 1
	v_add3_u32 v167, v167, v219, s52
	global_store_short_d16_hi v[20:21], v167, off offset:928
	s_waitcnt vmcnt(63)
	v_lshlrev_b32_e32 v168, 16, v168
	v_mul_f32_e32 v168, v26, v168
	v_bfe_u32 v220, v168, 16, 1
	v_add3_u32 v168, v168, v220, s52
	global_store_short_d16_hi v[20:21], v168, off offset:960
	s_waitcnt vmcnt(63)
	v_lshlrev_b32_e32 v169, 16, v169
	v_mul_f32_e32 v169, v26, v169
	v_bfe_u32 v221, v169, 16, 1
	v_add3_u32 v169, v169, v221, s52
	global_store_short_d16_hi v[20:21], v169, off offset:992
	s_waitcnt vmcnt(63)
	v_lshlrev_b32_e32 v170, 16, v170
	v_mul_f32_e32 v170, v27, v170
	v_bfe_u32 v218, v170, 16, 1
	v_add3_u32 v170, v170, v218, s52
	global_store_short_d16_hi v[22:23], v170, off offset:512
	s_waitcnt vmcnt(63)
	v_lshlrev_b32_e32 v171, 16, v171
	v_mul_f32_e32 v171, v27, v171
	v_bfe_u32 v219, v171, 16, 1
	v_add3_u32 v171, v171, v219, s52
	global_store_short_d16_hi v[22:23], v171, off offset:544
	s_waitcnt vmcnt(63)
	v_lshlrev_b32_e32 v204, 16, v204
	v_mul_f32_e32 v204, v27, v204
	v_bfe_u32 v220, v204, 16, 1
	v_add3_u32 v204, v204, v220, s52
	global_store_short_d16_hi v[22:23], v204, off offset:576
	s_waitcnt vmcnt(63)
	v_lshlrev_b32_e32 v205, 16, v205
	v_mul_f32_e32 v205, v27, v205
	v_bfe_u32 v221, v205, 16, 1
	v_add3_u32 v205, v205, v221, s52
	global_store_short_d16_hi v[22:23], v205, off offset:608
	s_waitcnt vmcnt(63)
	v_lshlrev_b32_e32 v206, 16, v206
	v_mul_f32_e32 v206, v27, v206
	v_bfe_u32 v218, v206, 16, 1
	v_add3_u32 v206, v206, v218, s52
	global_store_short_d16_hi v[22:23], v206, off offset:640
	s_waitcnt vmcnt(63)
	v_lshlrev_b32_e32 v207, 16, v207
	v_mul_f32_e32 v207, v27, v207
	v_bfe_u32 v219, v207, 16, 1
	v_add3_u32 v207, v207, v219, s52
	global_store_short_d16_hi v[22:23], v207, off offset:672
	s_waitcnt vmcnt(63)
	v_lshlrev_b32_e32 v208, 16, v208
	v_mul_f32_e32 v208, v27, v208
	v_bfe_u32 v220, v208, 16, 1
	v_add3_u32 v208, v208, v220, s52
	global_store_short_d16_hi v[22:23], v208, off offset:704
	s_waitcnt vmcnt(63)
	v_lshlrev_b32_e32 v209, 16, v209
	v_mul_f32_e32 v209, v27, v209
	v_bfe_u32 v221, v209, 16, 1
	v_add3_u32 v209, v209, v221, s52
	global_store_short_d16_hi v[22:23], v209, off offset:736
	s_waitcnt vmcnt(63)
	v_lshlrev_b32_e32 v210, 16, v210
	v_mul_f32_e32 v210, v27, v210
	v_bfe_u32 v218, v210, 16, 1
	v_add3_u32 v210, v210, v218, s52
	global_store_short_d16_hi v[22:23], v210, off offset:768
	s_waitcnt vmcnt(63)
	v_lshlrev_b32_e32 v211, 16, v211
	v_mul_f32_e32 v211, v27, v211
	v_bfe_u32 v219, v211, 16, 1
	v_add3_u32 v211, v211, v219, s52
	global_store_short_d16_hi v[22:23], v211, off offset:800
	s_waitcnt vmcnt(63)
	v_lshlrev_b32_e32 v212, 16, v212
	v_mul_f32_e32 v212, v27, v212
	v_bfe_u32 v220, v212, 16, 1
	v_add3_u32 v212, v212, v220, s52
	global_store_short_d16_hi v[22:23], v212, off offset:832
	s_waitcnt vmcnt(63)
	v_lshlrev_b32_e32 v213, 16, v213
	v_mul_f32_e32 v213, v27, v213
	v_bfe_u32 v221, v213, 16, 1
	v_add3_u32 v213, v213, v221, s52
	global_store_short_d16_hi v[22:23], v213, off offset:864
	s_waitcnt vmcnt(63)
	v_lshlrev_b32_e32 v214, 16, v214
	v_mul_f32_e32 v214, v27, v214
	v_bfe_u32 v218, v214, 16, 1
	v_add3_u32 v214, v214, v218, s52
	global_store_short_d16_hi v[22:23], v214, off offset:896
	s_waitcnt vmcnt(63)
	v_lshlrev_b32_e32 v215, 16, v215
	v_mul_f32_e32 v215, v27, v215
	v_bfe_u32 v219, v215, 16, 1
	v_add3_u32 v215, v215, v219, s52
	global_store_short_d16_hi v[22:23], v215, off offset:928
	s_waitcnt vmcnt(63)
	v_lshlrev_b32_e32 v216, 16, v216
	v_mul_f32_e32 v216, v27, v216
	v_bfe_u32 v220, v216, 16, 1
	v_add3_u32 v216, v216, v220, s52
	global_store_short_d16_hi v[22:23], v216, off offset:960
	s_waitcnt vmcnt(63)
	v_lshlrev_b32_e32 v217, 16, v217
	v_mul_f32_e32 v217, v27, v217
	v_bfe_u32 v221, v217, 16, 1
	v_add3_u32 v217, v217, v221, s52
	global_store_short_d16_hi v[22:23], v217, off offset:992
